# out-proj phase start: the 4 serialized row-statistic iterations (two dependent load round trips each) unrolled with all loads in flight; on top of the in-proj rows unroll and gMLP load de-serialisatio
# speedup vs baseline: 1.0041x; 1.0041x over previous
; #define LAS __attribute__((address_space(3)))
; __device__ __forceinline__ int lane_fresh() { int l; asm volatile("v_mbcnt_lo_u32_b32 %0, -1, 0\n\tv_mbcnt_hi_u32_b32 %0, -1, %0" : "=v"(l)); return l; }
; __device__ __forceinline__ float sum4(f32x4 v) { return (v[0] + v[1]) + (v[2] + v[3]); }
;     __device__ bool next(int i, Unit& u) const {
;         const long L = (long)i * G + c; if (L >= nwg) return false;
;         int wgid = (int)L; { const int q = nwg / NXCD, r = nwg % NXCD, xcd = wgid % NXCD, off = wgid / NXCD; wgid = (xcd < r ? xcd * (q + 1) : r * (q + 1) + (xcd - r) * q) + off; }
;         const int nig = WGM * nN, gid = wgid / nig, fm = gid * WGM, gsz = (nM - fm) < WGM ? (nM - fm) : WGM;
;         u.pm = fm + ((wgid % nig) % gsz); u.pn = (wgid % nig) / gsz; return true;
; template <class Sched>
; __device__ __forceinline__ void run_out_proj(LAS unsigned char* lds, const Params& p, int l, const Sched& S, int M, int rows_off, int wave) {
;     ...
;         const int ln = lane_fresh(), t = wave * 64 + ln, r = t >> 1, hf = t & 1;
;         LAS float* rows = (LAS float*)(lds + rows_off); pg8::Unit u;
;         for (int i = 0; i < 10 && S.next(i, u); ++i) {
;             const size_t row = (size_t)u.pm * 256 + r;
;             const f32x4* ap = (const f32x4*)(SSA + row * 16 + hf * 8); const f32x4* bp = (const f32x4*)(SSB + row * 32 + hf * 16);
;             float sa = sum4(ap[0]) + sum4(ap[1]), sb = (sum4(bp[0]) + sum4(bp[1])) + (sum4(bp[2]) + sum4(bp[3]));
;             sa += __shfl_xor(sa, 1); sb += __shfl_xor(sb, 1);
;             const float a = sa * (1.0f / 1024.0f) + EPS, b = sb * (1.0f / 1024.0f) + EPS;
;             if (hf == 0) { rows[i * 768 + r] = __builtin_sqrtf(a); rows[i * 768 + 256 + r] = __builtin_amdgcn_rsqf(a) * __builtin_sqrtf(b); rows[i * 768 + 512 + r] = __builtin_amdgcn_rsqf(b); }
;         }
.LBB0_619:
	s_or_b64 exec, exec, s[0:1]
	s_waitcnt lgkmcnt(0)
	s_barrier
	v_mbcnt_lo_u32_b32 v0, -1, 0
	v_mbcnt_hi_u32_b32 v0, -1, v0
	v_readlane_b32 s0, v253, 15
	v_and_b32_e32 v8, 1, v0
	v_add_u32_e32 v2, s6, v0
	v_lshlrev_b32_e32 v0, 5, v8
	v_readlane_b32 s1, v253, 16
	v_ashrrev_i32_e32 v2, 1, v2
	v_ashrrev_i32_e32 v3, 31, v2
	v_lshl_add_u64 v[4:5], s[0:1], 0, v[0:1]
	v_readlane_b32 s0, v253, 42
	v_lshlrev_b32_e32 v0, 6, v8
	v_readlane_b32 s1, v253, 43
	s_mov_b32 s7, 0
	v_cmp_eq_u32_e64 s[40:41], 0, v8
	v_lshl_add_u64 v[6:7], s[0:1], 0, v[0:1]
	v_lshl_add_u32 v0, v2, 2, 0
	s_mov_b64 s[8:9], s[2:3]
	v_cmp_lt_i32_e32 vcc, v187, v186
	s_nop 1
	v_cndmask_b32_e32 v120, v185, v187, vcc
	v_lshlrev_b32_e32 v120, 2, v120
	s_waitcnt lgkmcnt(0)
	s_ashr_i32 s0, s8, 31
	s_lshr_b32 s0, s0, 29
	s_add_i32 s10, s8, s0
	s_and_b32 s0, s10, -8
	s_sub_i32 s11, s8, s0
	s_lshl_b32 s12, s11, 7
	s_mul_i32 s13, s11, 0x81
	s_cmp_gt_i32 s11, -1
	s_cselect_b32 s12, s12, s13
	s_ashr_i32 s0, s10, 3
	s_add_i32 s0, s12, s0
	s_ashr_i32 s1, s0, 31
	s_lshr_b32 s1, s1, 27
	s_add_i32 s1, s0, s1
	s_ashr_i32 s10, s1, 5
	s_andn2_b32 s1, s1, 31
	s_sub_i32 s0, s0, s1
	s_lshl_b32 s1, s10, 2
	s_sub_i32 s10, 0x80, s1
	s_min_i32 s10, s10, 4
	s_abs_i32 s10, s10
	v_cvt_f32_u32_e32 v8, s10
	s_sub_i32 s12, 0, s10
	s_ashr_i32 s11, s0, 31
	s_abs_i32 s0, s0
	v_rcp_iflag_f32_e32 v8, v8
	s_nop 1
	v_mul_f32_e32 v8, 0x4f7ffffe, v8
	v_cvt_u32_f32_e32 v8, v8
	s_nop 1
	v_readfirstlane_b32 s13, v8
	s_mul_i32 s12, s12, s13
	s_mul_hi_u32 s12, s13, s12
	s_add_i32 s13, s13, s12
	s_mul_hi_u32 s12, s0, s13
	s_mul_i32 s12, s12, s10
	s_sub_i32 s0, s0, s12
	s_sub_i32 s12, s0, s10
	s_cmp_ge_u32 s0, s10
	s_cselect_b32 s0, s12, s0
	s_sub_i32 s12, s0, s10
	s_cmp_ge_u32 s0, s10
	s_cselect_b32 s0, s12, s0
	s_xor_b32 s0, s0, s11
	s_sub_i32 s0, s0, s11
	s_add_i32 s0, s1, s0
	s_ashr_i32 s1, s0, 31
	s_lshl_b64 s[0:1], s[0:1], 8
	v_lshl_add_u64 v[8:9], s[0:1], 0, v[2:3]
	v_lshlrev_b64 v[10:11], 6, v[8:9]
	v_lshl_add_u64 v[12:13], v[4:5], 0, v[10:11]
	v_lshlrev_b64 v[8:9], 7, v[8:9]
	v_lshl_add_u64 v[22:23], v[6:7], 0, v[8:9]
	global_load_dwordx4 v[24:27], v[12:13], off offset:16
	global_load_dwordx4 v[28:31], v[12:13], off
	global_load_dwordx4 v[32:35], v[22:23], off offset:48
	global_load_dwordx4 v[36:39], v[22:23], off offset:32
	global_load_dwordx4 v[40:43], v[22:23], off offset:16
	global_load_dwordx4 v[44:47], v[22:23], off
	s_add_u32 s8, s8, s88
	s_addc_u32 s9, s9, s31
	s_ashr_i32 s0, s8, 31
	s_lshr_b32 s0, s0, 29
	s_add_i32 s10, s8, s0
	s_and_b32 s0, s10, -8
	s_sub_i32 s11, s8, s0
	s_lshl_b32 s12, s11, 7
	s_mul_i32 s13, s11, 0x81
	s_cmp_gt_i32 s11, -1
	s_cselect_b32 s12, s12, s13
	s_ashr_i32 s0, s10, 3
	s_add_i32 s0, s12, s0
	s_ashr_i32 s1, s0, 31
	s_lshr_b32 s1, s1, 27
	s_add_i32 s1, s0, s1
	s_ashr_i32 s10, s1, 5
	s_andn2_b32 s1, s1, 31
	s_sub_i32 s0, s0, s1
	s_lshl_b32 s1, s10, 2
	s_sub_i32 s10, 0x80, s1
	s_min_i32 s10, s10, 4
	s_abs_i32 s10, s10
	v_cvt_f32_u32_e32 v8, s10
	s_sub_i32 s12, 0, s10
	s_ashr_i32 s11, s0, 31
	s_abs_i32 s0, s0
	v_rcp_iflag_f32_e32 v8, v8
	s_nop 1
	v_mul_f32_e32 v8, 0x4f7ffffe, v8
	v_cvt_u32_f32_e32 v8, v8
	s_nop 1
	v_readfirstlane_b32 s13, v8
	s_mul_i32 s12, s12, s13
	s_mul_hi_u32 s12, s13, s12
	s_add_i32 s13, s13, s12
	s_mul_hi_u32 s12, s0, s13
	s_mul_i32 s12, s12, s10
	s_sub_i32 s0, s0, s12
	s_sub_i32 s12, s0, s10
	s_cmp_ge_u32 s0, s10
	s_cselect_b32 s0, s12, s0
	s_sub_i32 s12, s0, s10
	s_cmp_ge_u32 s0, s10
	s_cselect_b32 s0, s12, s0
	s_xor_b32 s0, s0, s11
	s_sub_i32 s0, s0, s11
	s_add_i32 s0, s1, s0
	s_ashr_i32 s1, s0, 31
	s_lshl_b64 s[0:1], s[0:1], 8
	v_lshl_add_u64 v[8:9], s[0:1], 0, v[2:3]
	v_lshlrev_b64 v[10:11], 6, v[8:9]
	v_lshl_add_u64 v[12:13], v[4:5], 0, v[10:11]
	v_lshlrev_b64 v[8:9], 7, v[8:9]
	v_lshl_add_u64 v[22:23], v[6:7], 0, v[8:9]
	global_load_dwordx4 v[48:51], v[12:13], off offset:16
	global_load_dwordx4 v[52:55], v[12:13], off
	global_load_dwordx4 v[56:59], v[22:23], off offset:48
	global_load_dwordx4 v[60:63], v[22:23], off offset:32
	global_load_dwordx4 v[64:67], v[22:23], off offset:16
	global_load_dwordx4 v[68:71], v[22:23], off
	s_add_u32 s8, s8, s88
	s_addc_u32 s9, s9, s31
	s_ashr_i32 s0, s8, 31
	s_lshr_b32 s0, s0, 29
	s_add_i32 s10, s8, s0
	s_and_b32 s0, s10, -8
	s_sub_i32 s11, s8, s0
	s_lshl_b32 s12, s11, 7
	s_mul_i32 s13, s11, 0x81
	s_cmp_gt_i32 s11, -1
	s_cselect_b32 s12, s12, s13
	s_ashr_i32 s0, s10, 3
	s_add_i32 s0, s12, s0
	s_ashr_i32 s1, s0, 31
	s_lshr_b32 s1, s1, 27
	s_add_i32 s1, s0, s1
	s_ashr_i32 s10, s1, 5
	s_andn2_b32 s1, s1, 31
	s_sub_i32 s0, s0, s1
	s_lshl_b32 s1, s10, 2
	s_sub_i32 s10, 0x80, s1
	s_min_i32 s10, s10, 4
	s_abs_i32 s10, s10
	v_cvt_f32_u32_e32 v8, s10
	s_sub_i32 s12, 0, s10
	s_ashr_i32 s11, s0, 31
	s_abs_i32 s0, s0
	v_rcp_iflag_f32_e32 v8, v8
	s_nop 1
	v_mul_f32_e32 v8, 0x4f7ffffe, v8
	v_cvt_u32_f32_e32 v8, v8
	s_nop 1
	v_readfirstlane_b32 s13, v8
	s_mul_i32 s12, s12, s13
	s_mul_hi_u32 s12, s13, s12
	s_add_i32 s13, s13, s12
	s_mul_hi_u32 s12, s0, s13
	s_mul_i32 s12, s12, s10
	s_sub_i32 s0, s0, s12
	s_sub_i32 s12, s0, s10
	s_cmp_ge_u32 s0, s10
	s_cselect_b32 s0, s12, s0
	s_sub_i32 s12, s0, s10
	s_cmp_ge_u32 s0, s10
	s_cselect_b32 s0, s12, s0
	s_xor_b32 s0, s0, s11
	s_sub_i32 s0, s0, s11
	s_add_i32 s0, s1, s0
	s_ashr_i32 s1, s0, 31
	s_lshl_b64 s[0:1], s[0:1], 8
	v_lshl_add_u64 v[8:9], s[0:1], 0, v[2:3]
	v_lshlrev_b64 v[10:11], 6, v[8:9]
	v_lshl_add_u64 v[12:13], v[4:5], 0, v[10:11]
	v_lshlrev_b64 v[8:9], 7, v[8:9]
	v_lshl_add_u64 v[22:23], v[6:7], 0, v[8:9]
	global_load_dwordx4 v[72:75], v[12:13], off offset:16
	global_load_dwordx4 v[76:79], v[12:13], off
	global_load_dwordx4 v[80:83], v[22:23], off offset:48
; __device__ __forceinline__ float sum4(f32x4 v) { return (v[0] + v[1]) + (v[2] + v[3]); }
; template <class Sched>
; __device__ __forceinline__ void run_out_proj(LAS unsigned char* lds, const Params& p, int l, const Sched& S, int M, int rows_off, int wave) {
;     ...
;         for (int i = 0; i < 10 && S.next(i, u); ++i) {
;             const size_t row = (size_t)u.pm * 256 + r;
;             const f32x4* ap = (const f32x4*)(SSA + row * 16 + hf * 8); const f32x4* bp = (const f32x4*)(SSB + row * 32 + hf * 16);
;             float sa = sum4(ap[0]) + sum4(ap[1]), sb = (sum4(bp[0]) + sum4(bp[1])) + (sum4(bp[2]) + sum4(bp[3]));
;             sa += __shfl_xor(sa, 1); sb += __shfl_xor(sb, 1);
;             const float a = sa * (1.0f / 1024.0f) + EPS, b = sb * (1.0f / 1024.0f) + EPS;
;             if (hf == 0) { rows[i * 768 + r] = __builtin_sqrtf(a); rows[i * 768 + 256 + r] = __builtin_amdgcn_rsqf(a) * __builtin_sqrtf(b); rows[i * 768 + 512 + r] = __builtin_amdgcn_rsqf(b); }
	global_load_dwordx4 v[84:87], v[22:23], off offset:32
	global_load_dwordx4 v[88:91], v[22:23], off offset:16
	global_load_dwordx4 v[92:95], v[22:23], off
	s_add_u32 s8, s8, s88
	s_addc_u32 s9, s9, s31
	s_ashr_i32 s0, s8, 31
	s_lshr_b32 s0, s0, 29
	s_add_i32 s10, s8, s0
	s_and_b32 s0, s10, -8
	s_sub_i32 s11, s8, s0
	s_lshl_b32 s12, s11, 7
	s_mul_i32 s13, s11, 0x81
	s_cmp_gt_i32 s11, -1
	s_cselect_b32 s12, s12, s13
	s_ashr_i32 s0, s10, 3
	s_add_i32 s0, s12, s0
	s_ashr_i32 s1, s0, 31
	s_lshr_b32 s1, s1, 27
	s_add_i32 s1, s0, s1
	s_ashr_i32 s10, s1, 5
	s_andn2_b32 s1, s1, 31
	s_sub_i32 s0, s0, s1
	s_lshl_b32 s1, s10, 2
	s_sub_i32 s10, 0x80, s1
	s_min_i32 s10, s10, 4
	s_abs_i32 s10, s10
	v_cvt_f32_u32_e32 v8, s10
	s_sub_i32 s12, 0, s10
	s_ashr_i32 s11, s0, 31
	s_abs_i32 s0, s0
	v_rcp_iflag_f32_e32 v8, v8
	s_nop 1
	v_mul_f32_e32 v8, 0x4f7ffffe, v8
	v_cvt_u32_f32_e32 v8, v8
	s_nop 1
	v_readfirstlane_b32 s13, v8
	s_mul_i32 s12, s12, s13
	s_mul_hi_u32 s12, s13, s12
	s_add_i32 s13, s13, s12
	s_mul_hi_u32 s12, s0, s13
	s_mul_i32 s12, s12, s10
	s_sub_i32 s0, s0, s12
	s_sub_i32 s12, s0, s10
	s_cmp_ge_u32 s0, s10
	s_cselect_b32 s0, s12, s0
	s_sub_i32 s12, s0, s10
	s_cmp_ge_u32 s0, s10
	s_cselect_b32 s0, s12, s0
	s_xor_b32 s0, s0, s11
	s_sub_i32 s0, s0, s11
	s_add_i32 s0, s1, s0
	s_ashr_i32 s1, s0, 31
	s_lshl_b64 s[0:1], s[0:1], 8
	v_lshl_add_u64 v[8:9], s[0:1], 0, v[2:3]
	v_lshlrev_b64 v[10:11], 6, v[8:9]
	v_lshl_add_u64 v[12:13], v[4:5], 0, v[10:11]
	v_lshlrev_b64 v[8:9], 7, v[8:9]
	v_lshl_add_u64 v[22:23], v[6:7], 0, v[8:9]
	global_load_dwordx4 v[96:99], v[12:13], off offset:16
	global_load_dwordx4 v[100:103], v[12:13], off
	global_load_dwordx4 v[104:107], v[22:23], off offset:48
	global_load_dwordx4 v[108:111], v[22:23], off offset:32
	global_load_dwordx4 v[112:115], v[22:23], off offset:16
	global_load_dwordx4 v[116:119], v[22:23], off
	s_add_u32 s8, s8, s88
	s_addc_u32 s9, s9, s31
	s_waitcnt vmcnt(18)
	s_movk_i32 s7, 0x0
	v_add_f32_e32 v8, v24, v25
	v_add_f32_e32 v12, v28, v29
	v_add_f32_e32 v13, v30, v31
	v_add_f32_e32 v9, v26, v27
	v_add_f32_e32 v12, v12, v13
	v_add_f32_e32 v8, v8, v9
	v_add_f32_e32 v8, v12, v8
	v_add_f32_e32 v10, v32, v33
	v_add_f32_e32 v14, v36, v37
	v_add_f32_e32 v18, v40, v41
	v_add_f32_e32 v9, v44, v45
	v_add_f32_e32 v22, v46, v47
	v_add_f32_e32 v19, v42, v43
	v_add_f32_e32 v15, v38, v39
	v_add_f32_e32 v11, v34, v35
	v_add_f32_e32 v9, v9, v22
	v_add_f32_e32 v18, v18, v19
	v_add_f32_e32 v14, v14, v15
	v_add_f32_e32 v10, v10, v11
	v_add_f32_e32 v9, v9, v18
	v_add_f32_e32 v10, v14, v10
	v_add_f32_e32 v9, v9, v10
	s_nop 0
	ds_bpermute_b32 v11, v120, v8
	ds_bpermute_b32 v10, v120, v9
	s_and_saveexec_b64 s[10:11], s[40:41]
	s_cbranch_execz .Lmy_rows3_skip0
	s_waitcnt lgkmcnt(1)
	v_add_f32_e32 v8, v8, v11
	v_fmamk_f32 v8, v8, 0x3a800000, v184
	s_mov_b32 s4, 0xf800000
	v_mul_f32_e32 v11, 0x4f800000, v8
	v_cmp_gt_f32_e32 vcc, s4, v8
	s_waitcnt lgkmcnt(0)
	v_add_f32_e32 v9, v9, v10
	v_fmamk_f32 v9, v9, 0x3a800000, v184
	v_cndmask_b32_e32 v11, v8, v11, vcc
	v_sqrt_f32_e32 v12, v11
	v_rsq_f32_e32 v8, v8
	v_add_u32_e32 v10, -1, v12
	v_fma_f32 v13, -v10, v12, v11
	v_cmp_ge_f32_e64 s[0:1], 0, v13
	v_add_u32_e32 v13, 1, v12
	s_nop 0
	v_cndmask_b32_e64 v10, v12, v10, s[0:1]
	v_fma_f32 v12, -v13, v12, v11
	v_cmp_lt_f32_e64 s[0:1], 0, v12
	s_nop 1
	v_cndmask_b32_e64 v10, v10, v13, s[0:1]
	v_mul_f32_e32 v12, 0x37800000, v10
	v_cndmask_b32_e32 v10, v10, v12, vcc
	v_cmp_class_f32_e32 vcc, v11, v250
	v_mul_f32_e32 v12, 0x4f800000, v9
	s_nop 0
	v_cndmask_b32_e32 v10, v10, v11, vcc
	v_cmp_gt_f32_e32 vcc, s4, v9
	v_add_u32_e32 v11, s7, v0
	v_add_u32_e32 v14, 0x20000, v11
	v_cndmask_b32_e32 v12, v9, v12, vcc
	v_sqrt_f32_e32 v13, v12
	ds_write_b32 v14, v10
	v_rsq_f32_e32 v9, v9
	v_add_u32_e32 v10, -1, v13
	v_fma_f32 v14, -v10, v13, v12
	v_cmp_ge_f32_e64 s[0:1], 0, v14
	v_add_u32_e32 v14, 1, v13
	s_nop 0
	v_cndmask_b32_e64 v10, v13, v10, s[0:1]
	v_fma_f32 v13, -v14, v13, v12
	v_cmp_lt_f32_e64 s[0:1], 0, v13
	s_nop 1
	v_cndmask_b32_e64 v10, v10, v14, s[0:1]
	v_mul_f32_e32 v13, 0x37800000, v10
	v_cndmask_b32_e32 v10, v10, v13, vcc
	v_cmp_class_f32_e32 vcc, v12, v250
	s_nop 1
	v_cndmask_b32_e32 v10, v10, v12, vcc
	v_mul_f32_e32 v8, v8, v10
	v_add_u32_e32 v10, 0x20400, v11
	ds_write_b32 v10, v8
	v_add_u32_e32 v8, 0x20800, v11
	ds_write_b32 v8, v9
.Lmy_rows3_skip0:
	s_or_b64 exec, exec, s[10:11]
	s_waitcnt lgkmcnt(0)
	s_waitcnt vmcnt(12)
	s_movk_i32 s7, 0xc00
	v_add_f32_e32 v8, v48, v49
	v_add_f32_e32 v12, v52, v53
	v_add_f32_e32 v13, v54, v55
	v_add_f32_e32 v9, v50, v51
	v_add_f32_e32 v12, v12, v13
	v_add_f32_e32 v8, v8, v9
	v_add_f32_e32 v8, v12, v8
	v_add_f32_e32 v10, v56, v57
	v_add_f32_e32 v14, v60, v61
	v_add_f32_e32 v18, v64, v65
	v_add_f32_e32 v9, v68, v69
	v_add_f32_e32 v22, v70, v71
	v_add_f32_e32 v19, v66, v67
	v_add_f32_e32 v15, v62, v63
	v_add_f32_e32 v11, v58, v59
	v_add_f32_e32 v9, v9, v22
	v_add_f32_e32 v18, v18, v19
	v_add_f32_e32 v14, v14, v15
	v_add_f32_e32 v10, v10, v11
	v_add_f32_e32 v9, v9, v18
	v_add_f32_e32 v10, v14, v10
	v_add_f32_e32 v9, v9, v10
	s_nop 0
	ds_bpermute_b32 v11, v120, v8
	ds_bpermute_b32 v10, v120, v9
	s_and_saveexec_b64 s[10:11], s[40:41]
	s_cbranch_execz .Lmy_rows3_skip1
	s_waitcnt lgkmcnt(1)
	v_add_f32_e32 v8, v8, v11
	v_fmamk_f32 v8, v8, 0x3a800000, v184
	s_mov_b32 s4, 0xf800000
	v_mul_f32_e32 v11, 0x4f800000, v8
	v_cmp_gt_f32_e32 vcc, s4, v8
	s_waitcnt lgkmcnt(0)
	v_add_f32_e32 v9, v9, v10
	v_fmamk_f32 v9, v9, 0x3a800000, v184
	v_cndmask_b32_e32 v11, v8, v11, vcc
	v_sqrt_f32_e32 v12, v11
	v_rsq_f32_e32 v8, v8
	v_add_u32_e32 v10, -1, v12
	v_fma_f32 v13, -v10, v12, v11
	v_cmp_ge_f32_e64 s[0:1], 0, v13
	v_add_u32_e32 v13, 1, v12
	s_nop 0
	v_cndmask_b32_e64 v10, v12, v10, s[0:1]
	v_fma_f32 v12, -v13, v12, v11
	v_cmp_lt_f32_e64 s[0:1], 0, v12
	s_nop 1
	v_cndmask_b32_e64 v10, v10, v13, s[0:1]
	v_mul_f32_e32 v12, 0x37800000, v10
	v_cndmask_b32_e32 v10, v10, v12, vcc
	v_cmp_class_f32_e32 vcc, v11, v250
	v_mul_f32_e32 v12, 0x4f800000, v9
	s_nop 0
	v_cndmask_b32_e32 v10, v10, v11, vcc
	v_cmp_gt_f32_e32 vcc, s4, v9
	v_add_u32_e32 v11, s7, v0
	v_add_u32_e32 v14, 0x20000, v11
	v_cndmask_b32_e32 v12, v9, v12, vcc
	v_sqrt_f32_e32 v13, v12
	ds_write_b32 v14, v10
	v_rsq_f32_e32 v9, v9
	v_add_u32_e32 v10, -1, v13
	v_fma_f32 v14, -v10, v13, v12
	v_cmp_ge_f32_e64 s[0:1], 0, v14
	v_add_u32_e32 v14, 1, v13
	s_nop 0
	v_cndmask_b32_e64 v10, v13, v10, s[0:1]
	v_fma_f32 v13, -v14, v13, v12
	v_cmp_lt_f32_e64 s[0:1], 0, v13
	s_nop 1
	v_cndmask_b32_e64 v10, v10, v14, s[0:1]
	v_mul_f32_e32 v13, 0x37800000, v10
	v_cndmask_b32_e32 v10, v10, v13, vcc
	v_cmp_class_f32_e32 vcc, v12, v250
	s_nop 1
	v_cndmask_b32_e32 v10, v10, v12, vcc
	v_mul_f32_e32 v8, v8, v10
	v_add_u32_e32 v10, 0x20400, v11
	ds_write_b32 v10, v8
	v_add_u32_e32 v8, 0x20800, v11
	ds_write_b32 v8, v9
; __device__ __forceinline__ float sum4(f32x4 v) { return (v[0] + v[1]) + (v[2] + v[3]); }
; template <class Sched>
; __device__ __forceinline__ void run_out_proj(LAS unsigned char* lds, const Params& p, int l, const Sched& S, int M, int rows_off, int wave) {
;     ...
;         for (int i = 0; i < 10 && S.next(i, u); ++i) {
;             const size_t row = (size_t)u.pm * 256 + r;
;             const f32x4* ap = (const f32x4*)(SSA + row * 16 + hf * 8); const f32x4* bp = (const f32x4*)(SSB + row * 32 + hf * 16);
;             float sa = sum4(ap[0]) + sum4(ap[1]), sb = (sum4(bp[0]) + sum4(bp[1])) + (sum4(bp[2]) + sum4(bp[3]));
;             sa += __shfl_xor(sa, 1); sb += __shfl_xor(sb, 1);
;             const float a = sa * (1.0f / 1024.0f) + EPS, b = sb * (1.0f / 1024.0f) + EPS;
;             if (hf == 0) { rows[i * 768 + r] = __builtin_sqrtf(a); rows[i * 768 + 256 + r] = __builtin_amdgcn_rsqf(a) * __builtin_sqrtf(b); rows[i * 768 + 512 + r] = __builtin_amdgcn_rsqf(b); }
;         }
.Lmy_rows3_skip1:
	s_or_b64 exec, exec, s[10:11]
	s_waitcnt lgkmcnt(0)
	s_waitcnt vmcnt(6)
	s_movk_i32 s7, 0x1800
	v_add_f32_e32 v8, v72, v73
	v_add_f32_e32 v12, v76, v77
	v_add_f32_e32 v13, v78, v79
	v_add_f32_e32 v9, v74, v75
	v_add_f32_e32 v12, v12, v13
	v_add_f32_e32 v8, v8, v9
	v_add_f32_e32 v8, v12, v8
	v_add_f32_e32 v10, v80, v81
	v_add_f32_e32 v14, v84, v85
	v_add_f32_e32 v18, v88, v89
	v_add_f32_e32 v9, v92, v93
	v_add_f32_e32 v22, v94, v95
	v_add_f32_e32 v19, v90, v91
	v_add_f32_e32 v15, v86, v87
	v_add_f32_e32 v11, v82, v83
	v_add_f32_e32 v9, v9, v22
	v_add_f32_e32 v18, v18, v19
	v_add_f32_e32 v14, v14, v15
	v_add_f32_e32 v10, v10, v11
	v_add_f32_e32 v9, v9, v18
	v_add_f32_e32 v10, v14, v10
	v_add_f32_e32 v9, v9, v10
	s_nop 0
	ds_bpermute_b32 v11, v120, v8
	ds_bpermute_b32 v10, v120, v9
	s_and_saveexec_b64 s[10:11], s[40:41]
	s_cbranch_execz .Lmy_rows3_skip2
	s_waitcnt lgkmcnt(1)
	v_add_f32_e32 v8, v8, v11
	v_fmamk_f32 v8, v8, 0x3a800000, v184
	s_mov_b32 s4, 0xf800000
	v_mul_f32_e32 v11, 0x4f800000, v8
	v_cmp_gt_f32_e32 vcc, s4, v8
	s_waitcnt lgkmcnt(0)
	v_add_f32_e32 v9, v9, v10
	v_fmamk_f32 v9, v9, 0x3a800000, v184
	v_cndmask_b32_e32 v11, v8, v11, vcc
	v_sqrt_f32_e32 v12, v11
	v_rsq_f32_e32 v8, v8
	v_add_u32_e32 v10, -1, v12
	v_fma_f32 v13, -v10, v12, v11
	v_cmp_ge_f32_e64 s[0:1], 0, v13
	v_add_u32_e32 v13, 1, v12
	s_nop 0
	v_cndmask_b32_e64 v10, v12, v10, s[0:1]
	v_fma_f32 v12, -v13, v12, v11
	v_cmp_lt_f32_e64 s[0:1], 0, v12
	s_nop 1
	v_cndmask_b32_e64 v10, v10, v13, s[0:1]
	v_mul_f32_e32 v12, 0x37800000, v10
	v_cndmask_b32_e32 v10, v10, v12, vcc
	v_cmp_class_f32_e32 vcc, v11, v250
	v_mul_f32_e32 v12, 0x4f800000, v9
	s_nop 0
	v_cndmask_b32_e32 v10, v10, v11, vcc
	v_cmp_gt_f32_e32 vcc, s4, v9
	v_add_u32_e32 v11, s7, v0
	v_add_u32_e32 v14, 0x20000, v11
	v_cndmask_b32_e32 v12, v9, v12, vcc
	v_sqrt_f32_e32 v13, v12
	ds_write_b32 v14, v10
	v_rsq_f32_e32 v9, v9
	v_add_u32_e32 v10, -1, v13
	v_fma_f32 v14, -v10, v13, v12
	v_cmp_ge_f32_e64 s[0:1], 0, v14
	v_add_u32_e32 v14, 1, v13
	s_nop 0
	v_cndmask_b32_e64 v10, v13, v10, s[0:1]
	v_fma_f32 v13, -v14, v13, v12
	v_cmp_lt_f32_e64 s[0:1], 0, v13
	s_nop 1
	v_cndmask_b32_e64 v10, v10, v14, s[0:1]
	v_mul_f32_e32 v13, 0x37800000, v10
	v_cndmask_b32_e32 v10, v10, v13, vcc
	v_cmp_class_f32_e32 vcc, v12, v250
	s_nop 1
	v_cndmask_b32_e32 v10, v10, v12, vcc
	v_mul_f32_e32 v8, v8, v10
	v_add_u32_e32 v10, 0x20400, v11
	ds_write_b32 v10, v8
	v_add_u32_e32 v8, 0x20800, v11
	ds_write_b32 v8, v9
.Lmy_rows3_skip2:
	s_or_b64 exec, exec, s[10:11]
	s_waitcnt lgkmcnt(0)
	s_waitcnt vmcnt(0)
	s_movk_i32 s7, 0x2400
	v_add_f32_e32 v8, v96, v97
	v_add_f32_e32 v12, v100, v101
	v_add_f32_e32 v13, v102, v103
	v_add_f32_e32 v9, v98, v99
	v_add_f32_e32 v12, v12, v13
	v_add_f32_e32 v8, v8, v9
	v_add_f32_e32 v8, v12, v8
	v_add_f32_e32 v10, v104, v105
	v_add_f32_e32 v14, v108, v109
	v_add_f32_e32 v18, v112, v113
	v_add_f32_e32 v9, v116, v117
	v_add_f32_e32 v22, v118, v119
	v_add_f32_e32 v19, v114, v115
	v_add_f32_e32 v15, v110, v111
	v_add_f32_e32 v11, v106, v107
	v_add_f32_e32 v9, v9, v22
	v_add_f32_e32 v18, v18, v19
	v_add_f32_e32 v14, v14, v15
	v_add_f32_e32 v10, v10, v11
	v_add_f32_e32 v9, v9, v18
	v_add_f32_e32 v10, v14, v10
	v_add_f32_e32 v9, v9, v10
	s_nop 0
	ds_bpermute_b32 v11, v120, v8
	ds_bpermute_b32 v10, v120, v9
	s_and_saveexec_b64 s[10:11], s[40:41]
	s_cbranch_execz .Lmy_rows3_skip3
	s_waitcnt lgkmcnt(1)
	v_add_f32_e32 v8, v8, v11
	v_fmamk_f32 v8, v8, 0x3a800000, v184
	s_mov_b32 s4, 0xf800000
	v_mul_f32_e32 v11, 0x4f800000, v8
	v_cmp_gt_f32_e32 vcc, s4, v8
	s_waitcnt lgkmcnt(0)
	v_add_f32_e32 v9, v9, v10
	v_fmamk_f32 v9, v9, 0x3a800000, v184
	v_cndmask_b32_e32 v11, v8, v11, vcc
	v_sqrt_f32_e32 v12, v11
	v_rsq_f32_e32 v8, v8
	v_add_u32_e32 v10, -1, v12
	v_fma_f32 v13, -v10, v12, v11
	v_cmp_ge_f32_e64 s[0:1], 0, v13
	v_add_u32_e32 v13, 1, v12
	s_nop 0
	v_cndmask_b32_e64 v10, v12, v10, s[0:1]
	v_fma_f32 v12, -v13, v12, v11
	v_cmp_lt_f32_e64 s[0:1], 0, v12
	s_nop 1
	v_cndmask_b32_e64 v10, v10, v13, s[0:1]
	v_mul_f32_e32 v12, 0x37800000, v10
	v_cndmask_b32_e32 v10, v10, v12, vcc
	v_cmp_class_f32_e32 vcc, v11, v250
	v_mul_f32_e32 v12, 0x4f800000, v9
	s_nop 0
	v_cndmask_b32_e32 v10, v10, v11, vcc
	v_cmp_gt_f32_e32 vcc, s4, v9
	v_add_u32_e32 v11, s7, v0
	v_add_u32_e32 v14, 0x20000, v11
	v_cndmask_b32_e32 v12, v9, v12, vcc
	v_sqrt_f32_e32 v13, v12
	ds_write_b32 v14, v10
	v_rsq_f32_e32 v9, v9
	v_add_u32_e32 v10, -1, v13
	v_fma_f32 v14, -v10, v13, v12
	v_cmp_ge_f32_e64 s[0:1], 0, v14
	v_add_u32_e32 v14, 1, v13
	s_nop 0
	v_cndmask_b32_e64 v10, v13, v10, s[0:1]
	v_fma_f32 v13, -v14, v13, v12
	v_cmp_lt_f32_e64 s[0:1], 0, v13
	s_nop 1
	v_cndmask_b32_e64 v10, v10, v14, s[0:1]
	v_mul_f32_e32 v13, 0x37800000, v10
	v_cndmask_b32_e32 v10, v10, v13, vcc
	v_cmp_class_f32_e32 vcc, v12, v250
	s_nop 1
	v_cndmask_b32_e32 v10, v10, v12, vcc
	v_mul_f32_e32 v8, v8, v10
	v_add_u32_e32 v10, 0x20400, v11
	ds_write_b32 v10, v8
	v_add_u32_e32 v8, 0x20800, v11
	ds_write_b32 v8, v9
.Lmy_rows3_skip3:
	s_or_b64 exec, exec, s[10:11]
	s_waitcnt lgkmcnt(0)
	s_movk_i32 s7, 0x3000
	s_mov_b64 s[0:1], -1
